# EpiKV V-transposed scatter: token pairs packed via DPP so 128 2-byte stores per lane become 64 dword stores
# speedup vs baseline: 1.0093x; 1.0093x over previous
; __device__ __forceinline__ float rstd4(const float* pp, int row, float invn) { const f32x4 a = *(const f32x4*)(pp + (size_t)row * 4); return rsqrtf(((a.x + a.y) + (a.z + a.w)) * invn + 1e-6f); }
.LBB0_1097:
	v_mbcnt_lo_u32_b32 v237, -1, 0
	v_mbcnt_hi_u32_b32 v237, -1, v237
	v_and_b32_e32 v237, 1, v237
	v_mul_u32_u24_e32 v232, 0xffe, v237
	v_mov_b32_e32 v233, 0
	v_mov_b32_e32 v234, 0x2000
	v_mov_b32_e32 v235, 0
	v_mov_b32_e32 v236, 0x7060302
	v_mov_b32_e32 v238, 0x3020706
	v_cmp_ne_u32_e32 vcc, 0, v237
	s_nop 1
	v_cndmask_b32_e32 v236, v236, v238, vcc
	s_lshl_b32 s33, s45, 8
	s_add_i32 s33, s33, s92
	s_ashr_i32 s4, s33, 8
	s_lshl_b32 s50, s44, 1
	v_or_b32_e32 v154, s33, v137
	s_and_b32 s14, s4, -8
	v_readlane_b32 s4, v254, 12
	v_ashrrev_i32_e32 v155, 31, v154
	v_readlane_b32 s5, v254, 13
	s_nop 1
	v_lshl_add_u64 v[156:157], v[154:155], 4, s[4:5]
	v_mov_b32_e32 v218, v154
	v_ashrrev_i32_e32 v219, 31, v218
	v_lshl_add_u64 v[218:219], v[218:219], 4, s[4:5]
	global_load_dwordx4 v[186:189], v[218:219], off
	v_add_u32_e32 v218, 16, v154
	v_ashrrev_i32_e32 v219, 31, v218
	v_lshl_add_u64 v[218:219], v[218:219], 4, s[4:5]
	global_load_dwordx4 v[190:193], v[218:219], off
	v_add_u32_e32 v218, 32, v154
	v_ashrrev_i32_e32 v219, 31, v218
	v_lshl_add_u64 v[218:219], v[218:219], 4, s[4:5]
	global_load_dwordx4 v[194:197], v[218:219], off
	v_add_u32_e32 v218, 48, v154
	v_ashrrev_i32_e32 v219, 31, v218
	v_lshl_add_u64 v[218:219], v[218:219], 4, s[4:5]
	global_load_dwordx4 v[198:201], v[218:219], off
	v_add_u32_e32 v218, 128, v154
	v_ashrrev_i32_e32 v219, 31, v218
	v_lshl_add_u64 v[218:219], v[218:219], 4, s[4:5]
	global_load_dwordx4 v[202:205], v[218:219], off
	v_add_u32_e32 v218, 144, v154
	v_ashrrev_i32_e32 v219, 31, v218
	v_lshl_add_u64 v[218:219], v[218:219], 4, s[4:5]
	global_load_dwordx4 v[206:209], v[218:219], off
	v_add_u32_e32 v218, 160, v154
	v_ashrrev_i32_e32 v219, 31, v218
	v_lshl_add_u64 v[218:219], v[218:219], 4, s[4:5]
	global_load_dwordx4 v[210:213], v[218:219], off
	v_add_u32_e32 v218, 176, v154
	v_ashrrev_i32_e32 v219, 31, v218
	v_lshl_add_u64 v[218:219], v[218:219], 4, s[4:5]
	global_load_dwordx4 v[214:217], v[218:219], off
	s_waitcnt vmcnt(0)
	s_mov_b32 s4, 0x800000
	v_mov_b32_e32 v156, v186
	v_mov_b32_e32 v157, v187
	v_mov_b32_e32 v158, v188
	v_mov_b32_e32 v159, v189
	v_mov_b32_e32 v160, v157
	v_mov_b32_e32 v161, v158
	v_mov_b32_e32 v157, v159
	v_pk_add_f32 v[156:157], v[160:161], v[156:157]
	s_nop 0
	v_add_f32_e32 v144, v156, v157
	v_fmamk_f32 v144, v144, 0x3c000000, v171
	v_cmp_gt_f32_e32 vcc, s4, v144
	v_mul_f32_e32 v155, 0x4b800000, v144
	s_mov_b64 s[4:5], -1
	v_cndmask_b32_e32 v144, v144, v155, vcc
	v_rsq_f32_e32 v144, v144
	s_nop 0
	v_mul_f32_e32 v155, 0x45800000, v144
	v_cndmask_b32_e32 v156, v144, v155, vcc
	v_bitop3_b32 v144, s33, v178, v137 bitop3:0xc8
	v_pk_mul_f32 v[122:123], v[122:123], v[156:157] op_sel_hi:[1,0]
	v_pk_mul_f32 v[158:159], v[120:121], v[156:157] op_sel_hi:[1,0]
	v_pk_mul_f32 v[120:121], v[126:127], v[156:157] op_sel_hi:[1,0]
	v_pk_mul_f32 v[124:125], v[124:125], v[156:157] op_sel_hi:[1,0]
	s_and_b64 vcc, exec, s[24:25]
	v_lshlrev_b32_e32 v126, 1, v144
	s_cbranch_vccz .LBB0_1099
	s_add_i32 s4, s14, s50
	s_ashr_i32 s5, s4, 31
	s_lshl_b64 s[4:5], s[4:5], 18
	v_lshl_add_u64 v[160:161], v[138:139], 0, s[4:5]
	v_mov_b32_e32 v127, v145
	v_lshl_add_u64 v[160:161], v[160:161], 0, v[126:127]
	s_movk_i32 s4, 0x2000
	s_movk_i32 s4, 0x3000
	s_movk_i32 s4, 0x4000
	v_cmp_ne_u32_e32 vcc, 0, v237
	v_bfe_u32 v238, v158, 16, 1
	v_add3_u32 v158, v158, v238, s1
	v_bfe_u32 v238, v159, 16, 1
	v_add3_u32 v159, v159, v238, s1
	v_bfe_u32 v238, v122, 16, 1
	v_add3_u32 v122, v122, v238, s1
	v_bfe_u32 v238, v123, 16, 1
	v_add3_u32 v123, v123, v238, s1
	v_bfe_u32 v238, v124, 16, 1
	v_add3_u32 v124, v124, v238, s1
	v_bfe_u32 v238, v125, 16, 1
	v_add3_u32 v125, v125, v238, s1
	v_bfe_u32 v238, v120, 16, 1
	v_add3_u32 v120, v120, v238, s1
	v_bfe_u32 v238, v121, 16, 1
	v_add3_u32 v121, v121, v238, s1
	v_cndmask_b32_e32 v220, v158, v159, vcc
	v_cndmask_b32_e32 v224, v159, v158, vcc
	v_cndmask_b32_e32 v221, v122, v123, vcc
	v_cndmask_b32_e32 v225, v123, v122, vcc
	v_cndmask_b32_e32 v222, v124, v125, vcc
	v_cndmask_b32_e32 v226, v125, v124, vcc
	v_cndmask_b32_e32 v223, v120, v121, vcc
	v_cndmask_b32_e32 v227, v121, v120, vcc
	v_lshl_add_u64 v[228:229], v[160:161], 0, v[232:233]
	v_mov_b32_dpp v224, v224 quad_perm:[1,0,3,2] row_mask:0xf bank_mask:0xf
	v_mov_b32_dpp v225, v225 quad_perm:[1,0,3,2] row_mask:0xf bank_mask:0xf
	v_mov_b32_dpp v226, v226 quad_perm:[1,0,3,2] row_mask:0xf bank_mask:0xf
	v_mov_b32_dpp v227, v227 quad_perm:[1,0,3,2] row_mask:0xf bank_mask:0xf
	s_nop 0
	v_perm_b32 v220, v224, v220, v236
	global_store_dword v[228:229], v220, off
	v_lshl_add_u64 v[228:229], v[228:229], 0, v[234:235]
	v_perm_b32 v221, v225, v221, v236
	global_store_dword v[228:229], v221, off
	v_lshl_add_u64 v[228:229], v[228:229], 0, v[234:235]
	v_perm_b32 v222, v226, v222, v236
	global_store_dword v[228:229], v222, off
	v_lshl_add_u64 v[228:229], v[228:229], 0, v[234:235]
	v_perm_b32 v223, v227, v223, v236
	global_store_dword v[228:229], v223, off
	s_mov_b64 s[4:5], 0

.LBB0_1101:
	v_mov_b32_e32 v120, v156
	v_mov_b32_e32 v121, v156
	v_mov_b32_e32 v157, v156
	v_pk_mul_f32 v[118:119], v[118:119], v[120:121]
	v_pk_mul_f32 v[114:115], v[114:115], v[120:121]
	v_cndmask_b32_e64 v120, 0, 1, s[24:25]
	s_or_b32 s51, s50, 1
	v_pk_mul_f32 v[116:117], v[116:117], v[156:157]
	v_pk_mul_f32 v[112:113], v[112:113], v[156:157]
	v_cmp_ne_u32_e64 s[4:5], 1, v120
	s_andn2_b64 vcc, exec, s[24:25]
	s_mov_b64 s[34:35], -1
	s_cbranch_vccnz .LBB0_1103
	s_add_i32 s34, s14, s51
	s_ashr_i32 s35, s34, 31
	s_lshl_b64 s[34:35], s[34:35], 18
	v_lshl_add_u64 v[120:121], v[138:139], 0, s[34:35]
	v_mov_b32_e32 v127, v145
	v_lshl_add_u64 v[120:121], v[120:121], 0, v[126:127]
	s_movk_i32 s15, 0x1000
	s_movk_i32 s15, 0x2000
	s_movk_i32 s15, 0x3000
	s_movk_i32 s15, 0x4000
	s_mov_b64 s[34:35], 0
	v_cmp_ne_u32_e32 vcc, 0, v237
	v_bfe_u32 v238, v116, 16, 1
	v_add3_u32 v116, v116, v238, s1
	v_bfe_u32 v238, v117, 16, 1
	v_add3_u32 v117, v117, v238, s1
	v_bfe_u32 v238, v118, 16, 1
	v_add3_u32 v118, v118, v238, s1
	v_bfe_u32 v238, v119, 16, 1
	v_add3_u32 v119, v119, v238, s1
	v_bfe_u32 v238, v112, 16, 1
	v_add3_u32 v112, v112, v238, s1
	v_bfe_u32 v238, v113, 16, 1
	v_add3_u32 v113, v113, v238, s1
	v_bfe_u32 v238, v114, 16, 1
	v_add3_u32 v114, v114, v238, s1
	v_bfe_u32 v238, v115, 16, 1
	v_add3_u32 v115, v115, v238, s1
	v_cndmask_b32_e32 v220, v116, v117, vcc
	v_cndmask_b32_e32 v224, v117, v116, vcc
	v_cndmask_b32_e32 v221, v118, v119, vcc
	v_cndmask_b32_e32 v225, v119, v118, vcc
	v_cndmask_b32_e32 v222, v112, v113, vcc
	v_cndmask_b32_e32 v226, v113, v112, vcc
	v_cndmask_b32_e32 v223, v114, v115, vcc
	v_cndmask_b32_e32 v227, v115, v114, vcc
	v_lshl_add_u64 v[228:229], v[120:121], 0, v[232:233]
	v_mov_b32_dpp v224, v224 quad_perm:[1,0,3,2] row_mask:0xf bank_mask:0xf
	v_mov_b32_dpp v225, v225 quad_perm:[1,0,3,2] row_mask:0xf bank_mask:0xf
	v_mov_b32_dpp v226, v226 quad_perm:[1,0,3,2] row_mask:0xf bank_mask:0xf
	v_mov_b32_dpp v227, v227 quad_perm:[1,0,3,2] row_mask:0xf bank_mask:0xf
	s_nop 0
	v_perm_b32 v220, v224, v220, v236
	global_store_dword v[228:229], v220, off
	v_lshl_add_u64 v[228:229], v[228:229], 0, v[234:235]
	v_perm_b32 v221, v225, v221, v236
	global_store_dword v[228:229], v221, off
	v_lshl_add_u64 v[228:229], v[228:229], 0, v[234:235]
	v_perm_b32 v222, v226, v222, v236
	global_store_dword v[228:229], v222, off
	v_lshl_add_u64 v[228:229], v[228:229], 0, v[234:235]
	v_perm_b32 v223, v227, v223, v236
	global_store_dword v[228:229], v223, off

; __device__ __forceinline__ float rstd4(const float* pp, int row, float invn) { const f32x4 a = *(const f32x4*)(pp + (size_t)row * 4); return rsqrtf(((a.x + a.y) + (a.z + a.w)) * invn + 1e-6f); }
.LBB0_1105:
	v_or_b32_e32 v114, 16, v154
	v_readlane_b32 s44, v254, 12
	v_ashrrev_i32_e32 v115, 31, v114
	v_readlane_b32 s45, v254, 13
	s_mov_b32 s15, 0x800000
	s_nop 0
	v_lshl_add_u64 v[112:113], v[114:115], 4, s[44:45]
	s_mov_b64 s[44:45], -1
	v_mov_b32_e32 v116, v190
	v_mov_b32_e32 v117, v191
	v_mov_b32_e32 v118, v192
	v_mov_b32_e32 v119, v193
	v_mov_b32_e32 v112, v117
	v_mov_b32_e32 v113, v118
	v_mov_b32_e32 v117, v119
	v_pk_add_f32 v[112:113], v[112:113], v[116:117]
	s_nop 0
	v_add_f32_e32 v112, v112, v113
	v_fmamk_f32 v112, v112, 0x3c000000, v171
	v_cmp_gt_f32_e32 vcc, s15, v112
	v_mul_f32_e32 v113, 0x4b800000, v112
	s_movk_i32 s15, 0x7df
	v_cndmask_b32_e32 v112, v112, v113, vcc
	v_rsq_f32_e32 v112, v112
	s_nop 0
	v_mul_f32_e32 v113, 0x45800000, v112
	v_cndmask_b32_e32 v112, v112, v113, vcc
	v_bitop3_b32 v113, v154, s15, 16 bitop3:0xc8
	v_pk_mul_f32 v[110:111], v[110:111], v[112:113] op_sel_hi:[1,0]
	v_pk_mul_f32 v[108:109], v[108:109], v[112:113] op_sel_hi:[1,0]
	v_pk_mul_f32 v[106:107], v[106:107], v[112:113] op_sel_hi:[1,0]
	v_pk_mul_f32 v[104:105], v[104:105], v[112:113] op_sel_hi:[1,0]
	s_and_b64 vcc, exec, s[4:5]
	v_lshlrev_b32_e32 v116, 1, v113
	s_cbranch_vccnz .LBB0_1107
	s_add_i32 s44, s14, s50
	s_ashr_i32 s45, s44, 31
	s_lshl_b64 s[44:45], s[44:45], 18
	v_lshl_add_u64 v[118:119], v[138:139], 0, s[44:45]
	v_mov_b32_e32 v117, v145
	v_lshl_add_u64 v[118:119], v[118:119], 0, v[116:117]
	s_movk_i32 s15, 0x1000
	s_movk_i32 s15, 0x2000
	s_movk_i32 s15, 0x3000
	s_movk_i32 s15, 0x4000
	s_mov_b64 s[44:45], 0
	v_cmp_ne_u32_e32 vcc, 0, v237
	v_bfe_u32 v238, v108, 16, 1
	v_add3_u32 v108, v108, v238, s1
	v_bfe_u32 v238, v109, 16, 1
	v_add3_u32 v109, v109, v238, s1
	v_bfe_u32 v238, v110, 16, 1
	v_add3_u32 v110, v110, v238, s1
	v_bfe_u32 v238, v111, 16, 1
	v_add3_u32 v111, v111, v238, s1
	v_bfe_u32 v238, v104, 16, 1
	v_add3_u32 v104, v104, v238, s1
	v_bfe_u32 v238, v105, 16, 1
	v_add3_u32 v105, v105, v238, s1
	v_bfe_u32 v238, v106, 16, 1
	v_add3_u32 v106, v106, v238, s1
	v_bfe_u32 v238, v107, 16, 1
	v_add3_u32 v107, v107, v238, s1
	v_cndmask_b32_e32 v220, v108, v109, vcc
	v_cndmask_b32_e32 v224, v109, v108, vcc
	v_cndmask_b32_e32 v221, v110, v111, vcc
	v_cndmask_b32_e32 v225, v111, v110, vcc
	v_cndmask_b32_e32 v222, v104, v105, vcc
	v_cndmask_b32_e32 v226, v105, v104, vcc
	v_cndmask_b32_e32 v223, v106, v107, vcc
	v_cndmask_b32_e32 v227, v107, v106, vcc
	v_lshl_add_u64 v[228:229], v[118:119], 0, v[232:233]
	v_mov_b32_dpp v224, v224 quad_perm:[1,0,3,2] row_mask:0xf bank_mask:0xf
	v_mov_b32_dpp v225, v225 quad_perm:[1,0,3,2] row_mask:0xf bank_mask:0xf
	v_mov_b32_dpp v226, v226 quad_perm:[1,0,3,2] row_mask:0xf bank_mask:0xf
	v_mov_b32_dpp v227, v227 quad_perm:[1,0,3,2] row_mask:0xf bank_mask:0xf
	s_nop 0
	v_perm_b32 v220, v224, v220, v236
	global_store_dword v[228:229], v220, off
	v_lshl_add_u64 v[228:229], v[228:229], 0, v[234:235]
	v_perm_b32 v221, v225, v221, v236
	global_store_dword v[228:229], v221, off
	v_lshl_add_u64 v[228:229], v[228:229], 0, v[234:235]
	v_perm_b32 v222, v226, v222, v236
	global_store_dword v[228:229], v222, off
	v_lshl_add_u64 v[228:229], v[228:229], 0, v[234:235]
	v_perm_b32 v223, v227, v223, v236
	global_store_dword v[228:229], v223, off

.LBB0_1109:
	v_mov_b32_e32 v113, v112
	v_mov_b32_e32 v104, v112
	v_mov_b32_e32 v105, v112
	v_pk_mul_f32 v[102:103], v[102:103], v[104:105]
	v_pk_mul_f32 v[100:101], v[100:101], v[112:113]
	v_pk_mul_f32 v[98:99], v[98:99], v[104:105]
	v_pk_mul_f32 v[96:97], v[96:97], v[112:113]
	s_and_b64 vcc, exec, s[4:5]
	s_mov_b64 s[44:45], -1
	s_cbranch_vccnz .LBB0_1111
	s_add_i32 s44, s14, s51
	s_ashr_i32 s45, s44, 31
	s_lshl_b64 s[44:45], s[44:45], 18
	v_lshl_add_u64 v[104:105], v[138:139], 0, s[44:45]
	v_mov_b32_e32 v117, v145
	v_lshl_add_u64 v[104:105], v[104:105], 0, v[116:117]
	s_movk_i32 s15, 0x1000
	s_movk_i32 s15, 0x2000
	s_movk_i32 s15, 0x3000
	s_movk_i32 s15, 0x4000
	s_mov_b64 s[44:45], 0
	v_cmp_ne_u32_e32 vcc, 0, v237
	v_bfe_u32 v238, v100, 16, 1
	v_add3_u32 v100, v100, v238, s1
	v_bfe_u32 v238, v101, 16, 1
	v_add3_u32 v101, v101, v238, s1
	v_bfe_u32 v238, v102, 16, 1
	v_add3_u32 v102, v102, v238, s1
	v_bfe_u32 v238, v103, 16, 1
	v_add3_u32 v103, v103, v238, s1
	v_bfe_u32 v238, v96, 16, 1
	v_add3_u32 v96, v96, v238, s1
	v_bfe_u32 v238, v97, 16, 1
	v_add3_u32 v97, v97, v238, s1
	v_bfe_u32 v238, v98, 16, 1
	v_add3_u32 v98, v98, v238, s1
	v_bfe_u32 v238, v99, 16, 1
	v_add3_u32 v99, v99, v238, s1
	v_cndmask_b32_e32 v220, v100, v101, vcc
	v_cndmask_b32_e32 v224, v101, v100, vcc
	v_cndmask_b32_e32 v221, v102, v103, vcc
	v_cndmask_b32_e32 v225, v103, v102, vcc
	v_cndmask_b32_e32 v222, v96, v97, vcc
	v_cndmask_b32_e32 v226, v97, v96, vcc
	v_cndmask_b32_e32 v223, v98, v99, vcc
	v_cndmask_b32_e32 v227, v99, v98, vcc
	v_lshl_add_u64 v[228:229], v[104:105], 0, v[232:233]
	v_mov_b32_dpp v224, v224 quad_perm:[1,0,3,2] row_mask:0xf bank_mask:0xf
	v_mov_b32_dpp v225, v225 quad_perm:[1,0,3,2] row_mask:0xf bank_mask:0xf
	v_mov_b32_dpp v226, v226 quad_perm:[1,0,3,2] row_mask:0xf bank_mask:0xf
	v_mov_b32_dpp v227, v227 quad_perm:[1,0,3,2] row_mask:0xf bank_mask:0xf
	s_nop 0
	v_perm_b32 v220, v224, v220, v236
	global_store_dword v[228:229], v220, off
	v_lshl_add_u64 v[228:229], v[228:229], 0, v[234:235]
	v_perm_b32 v221, v225, v221, v236
	global_store_dword v[228:229], v221, off
	v_lshl_add_u64 v[228:229], v[228:229], 0, v[234:235]
	v_perm_b32 v222, v226, v222, v236
	global_store_dword v[228:229], v222, off
	v_lshl_add_u64 v[228:229], v[228:229], 0, v[234:235]
	v_perm_b32 v223, v227, v223, v236
	global_store_dword v[228:229], v223, off

; __device__ __forceinline__ float rstd4(const float* pp, int row, float invn) { const f32x4 a = *(const f32x4*)(pp + (size_t)row * 4); return rsqrtf(((a.x + a.y) + (a.z + a.w)) * invn + 1e-6f); }
.LBB0_1113:
	v_or_b32_e32 v98, 32, v154
	v_readlane_b32 s44, v254, 12
	v_ashrrev_i32_e32 v99, 31, v98
	v_readlane_b32 s45, v254, 13
	s_mov_b32 s15, 0x800000
	s_nop 0
	v_lshl_add_u64 v[96:97], v[98:99], 4, s[44:45]
	s_mov_b64 s[44:45], -1
	v_mov_b32_e32 v100, v194
	v_mov_b32_e32 v101, v195
	v_mov_b32_e32 v102, v196
	v_mov_b32_e32 v103, v197
	v_mov_b32_e32 v96, v101
	v_mov_b32_e32 v97, v102
	v_mov_b32_e32 v101, v103
	v_pk_add_f32 v[96:97], v[96:97], v[100:101]
	s_nop 0
	v_add_f32_e32 v96, v96, v97
	v_fmamk_f32 v96, v96, 0x3c000000, v171
	v_cmp_gt_f32_e32 vcc, s15, v96
	v_mul_f32_e32 v97, 0x4b800000, v96
	s_movk_i32 s15, 0x7ef
	v_cndmask_b32_e32 v96, v96, v97, vcc
	v_rsq_f32_e32 v96, v96
	s_nop 0
	v_mul_f32_e32 v97, 0x45800000, v96
	v_cndmask_b32_e32 v96, v96, v97, vcc
	v_bitop3_b32 v97, v154, s15, 32 bitop3:0xc8
	v_pk_mul_f32 v[94:95], v[94:95], v[96:97] op_sel_hi:[1,0]
	v_pk_mul_f32 v[92:93], v[92:93], v[96:97] op_sel_hi:[1,0]
	v_pk_mul_f32 v[90:91], v[90:91], v[96:97] op_sel_hi:[1,0]
	v_pk_mul_f32 v[88:89], v[88:89], v[96:97] op_sel_hi:[1,0]
	s_and_b64 vcc, exec, s[4:5]
	v_lshlrev_b32_e32 v100, 1, v97
	s_cbranch_vccnz .LBB0_1115
	s_add_i32 s44, s14, s50
	s_ashr_i32 s45, s44, 31
	s_lshl_b64 s[44:45], s[44:45], 18
	v_lshl_add_u64 v[102:103], v[138:139], 0, s[44:45]
	v_mov_b32_e32 v101, v145
	v_lshl_add_u64 v[102:103], v[102:103], 0, v[100:101]
	s_movk_i32 s15, 0x1000
	s_movk_i32 s15, 0x2000
	s_movk_i32 s15, 0x3000
	s_movk_i32 s15, 0x4000
	s_mov_b64 s[44:45], 0
	v_cmp_ne_u32_e32 vcc, 0, v237
	v_bfe_u32 v238, v92, 16, 1
	v_add3_u32 v92, v92, v238, s1
	v_bfe_u32 v238, v93, 16, 1
	v_add3_u32 v93, v93, v238, s1
	v_bfe_u32 v238, v94, 16, 1
	v_add3_u32 v94, v94, v238, s1
	v_bfe_u32 v238, v95, 16, 1
	v_add3_u32 v95, v95, v238, s1
	v_bfe_u32 v238, v88, 16, 1
	v_add3_u32 v88, v88, v238, s1
	v_bfe_u32 v238, v89, 16, 1
	v_add3_u32 v89, v89, v238, s1
	v_bfe_u32 v238, v90, 16, 1
	v_add3_u32 v90, v90, v238, s1
	v_bfe_u32 v238, v91, 16, 1
	v_add3_u32 v91, v91, v238, s1
	v_cndmask_b32_e32 v220, v92, v93, vcc
	v_cndmask_b32_e32 v224, v93, v92, vcc
	v_cndmask_b32_e32 v221, v94, v95, vcc
	v_cndmask_b32_e32 v225, v95, v94, vcc
	v_cndmask_b32_e32 v222, v88, v89, vcc
	v_cndmask_b32_e32 v226, v89, v88, vcc
	v_cndmask_b32_e32 v223, v90, v91, vcc
	v_cndmask_b32_e32 v227, v91, v90, vcc
	v_lshl_add_u64 v[228:229], v[102:103], 0, v[232:233]
	v_mov_b32_dpp v224, v224 quad_perm:[1,0,3,2] row_mask:0xf bank_mask:0xf
	v_mov_b32_dpp v225, v225 quad_perm:[1,0,3,2] row_mask:0xf bank_mask:0xf
	v_mov_b32_dpp v226, v226 quad_perm:[1,0,3,2] row_mask:0xf bank_mask:0xf
	v_mov_b32_dpp v227, v227 quad_perm:[1,0,3,2] row_mask:0xf bank_mask:0xf
	s_nop 0
	v_perm_b32 v220, v224, v220, v236
	global_store_dword v[228:229], v220, off
	v_lshl_add_u64 v[228:229], v[228:229], 0, v[234:235]
	v_perm_b32 v221, v225, v221, v236
	global_store_dword v[228:229], v221, off
	v_lshl_add_u64 v[228:229], v[228:229], 0, v[234:235]
	v_perm_b32 v222, v226, v222, v236
	global_store_dword v[228:229], v222, off
	v_lshl_add_u64 v[228:229], v[228:229], 0, v[234:235]
	v_perm_b32 v223, v227, v223, v236
	global_store_dword v[228:229], v223, off

.LBB0_1117:
	v_mov_b32_e32 v97, v96
	v_mov_b32_e32 v88, v96
	v_mov_b32_e32 v89, v96
	v_pk_mul_f32 v[86:87], v[86:87], v[88:89]
	v_pk_mul_f32 v[84:85], v[84:85], v[96:97]
	v_pk_mul_f32 v[82:83], v[82:83], v[88:89]
	v_pk_mul_f32 v[80:81], v[80:81], v[96:97]
	s_and_b64 vcc, exec, s[4:5]
	s_mov_b64 s[44:45], -1
	s_cbranch_vccnz .LBB0_1119
	s_add_i32 s44, s14, s51
	s_ashr_i32 s45, s44, 31
	s_lshl_b64 s[44:45], s[44:45], 18
	v_lshl_add_u64 v[88:89], v[138:139], 0, s[44:45]
	v_mov_b32_e32 v101, v145
	v_lshl_add_u64 v[88:89], v[88:89], 0, v[100:101]
	s_movk_i32 s15, 0x1000
	s_movk_i32 s15, 0x2000
	s_movk_i32 s15, 0x3000
	s_movk_i32 s15, 0x4000
	s_mov_b64 s[44:45], 0
	v_cmp_ne_u32_e32 vcc, 0, v237
	v_bfe_u32 v238, v84, 16, 1
	v_add3_u32 v84, v84, v238, s1
	v_bfe_u32 v238, v85, 16, 1
	v_add3_u32 v85, v85, v238, s1
	v_bfe_u32 v238, v86, 16, 1
	v_add3_u32 v86, v86, v238, s1
	v_bfe_u32 v238, v87, 16, 1
	v_add3_u32 v87, v87, v238, s1
	v_bfe_u32 v238, v80, 16, 1
	v_add3_u32 v80, v80, v238, s1
	v_bfe_u32 v238, v81, 16, 1
	v_add3_u32 v81, v81, v238, s1
	v_bfe_u32 v238, v82, 16, 1
	v_add3_u32 v82, v82, v238, s1
	v_bfe_u32 v238, v83, 16, 1
	v_add3_u32 v83, v83, v238, s1
	v_cndmask_b32_e32 v220, v84, v85, vcc
	v_cndmask_b32_e32 v224, v85, v84, vcc
	v_cndmask_b32_e32 v221, v86, v87, vcc
	v_cndmask_b32_e32 v225, v87, v86, vcc
	v_cndmask_b32_e32 v222, v80, v81, vcc
	v_cndmask_b32_e32 v226, v81, v80, vcc
	v_cndmask_b32_e32 v223, v82, v83, vcc
	v_cndmask_b32_e32 v227, v83, v82, vcc
	v_lshl_add_u64 v[228:229], v[88:89], 0, v[232:233]
	v_mov_b32_dpp v224, v224 quad_perm:[1,0,3,2] row_mask:0xf bank_mask:0xf
	v_mov_b32_dpp v225, v225 quad_perm:[1,0,3,2] row_mask:0xf bank_mask:0xf
	v_mov_b32_dpp v226, v226 quad_perm:[1,0,3,2] row_mask:0xf bank_mask:0xf
	v_mov_b32_dpp v227, v227 quad_perm:[1,0,3,2] row_mask:0xf bank_mask:0xf
	s_nop 0
	v_perm_b32 v220, v224, v220, v236
	global_store_dword v[228:229], v220, off
	v_lshl_add_u64 v[228:229], v[228:229], 0, v[234:235]
	v_perm_b32 v221, v225, v221, v236
	global_store_dword v[228:229], v221, off
	v_lshl_add_u64 v[228:229], v[228:229], 0, v[234:235]
	v_perm_b32 v222, v226, v222, v236
	global_store_dword v[228:229], v222, off
	v_lshl_add_u64 v[228:229], v[228:229], 0, v[234:235]
	v_perm_b32 v223, v227, v223, v236
	global_store_dword v[228:229], v223, off

; __device__ __forceinline__ float rstd4(const float* pp, int row, float invn) { const f32x4 a = *(const f32x4*)(pp + (size_t)row * 4); return rsqrtf(((a.x + a.y) + (a.z + a.w)) * invn + 1e-6f); }
.LBB0_1121:
	v_or_b32_e32 v82, 48, v154
	v_readlane_b32 s44, v254, 12
	v_ashrrev_i32_e32 v83, 31, v82
	v_readlane_b32 s45, v254, 13
	s_mov_b32 s15, 0x800000
	s_nop 0
	v_lshl_add_u64 v[80:81], v[82:83], 4, s[44:45]
	s_mov_b64 s[44:45], -1
	v_mov_b32_e32 v84, v198
	v_mov_b32_e32 v85, v199
	v_mov_b32_e32 v86, v200
	v_mov_b32_e32 v87, v201
	v_mov_b32_e32 v80, v85
	v_mov_b32_e32 v81, v86
	v_mov_b32_e32 v85, v87
	v_pk_add_f32 v[80:81], v[80:81], v[84:85]
	s_nop 0
	v_add_f32_e32 v80, v80, v81
	v_fmamk_f32 v80, v80, 0x3c000000, v171
	v_cmp_gt_f32_e32 vcc, s15, v80
	v_mul_f32_e32 v81, 0x4b800000, v80
	s_movk_i32 s15, 0x7ff
	v_cndmask_b32_e32 v80, v80, v81, vcc
	v_rsq_f32_e32 v80, v80
	s_nop 0
	v_mul_f32_e32 v81, 0x45800000, v80
	v_cndmask_b32_e32 v80, v80, v81, vcc
	v_bitop3_b32 v81, v154, s15, 48 bitop3:0xc8
	v_pk_mul_f32 v[78:79], v[78:79], v[80:81] op_sel_hi:[1,0]
	v_pk_mul_f32 v[76:77], v[76:77], v[80:81] op_sel_hi:[1,0]
	v_pk_mul_f32 v[74:75], v[74:75], v[80:81] op_sel_hi:[1,0]
	v_pk_mul_f32 v[72:73], v[72:73], v[80:81] op_sel_hi:[1,0]
	s_and_b64 vcc, exec, s[4:5]
	v_lshlrev_b32_e32 v84, 1, v81
	s_cbranch_vccnz .LBB0_1123
	s_add_i32 s44, s14, s50
	s_ashr_i32 s45, s44, 31
	s_lshl_b64 s[44:45], s[44:45], 18
	v_lshl_add_u64 v[86:87], v[138:139], 0, s[44:45]
	v_mov_b32_e32 v85, v145
	v_lshl_add_u64 v[86:87], v[86:87], 0, v[84:85]
	s_movk_i32 s15, 0x1000
	s_movk_i32 s15, 0x2000
	s_movk_i32 s15, 0x3000
	s_movk_i32 s15, 0x4000
	s_mov_b64 s[44:45], 0
	v_cmp_ne_u32_e32 vcc, 0, v237
	v_bfe_u32 v238, v76, 16, 1
	v_add3_u32 v76, v76, v238, s1
	v_bfe_u32 v238, v77, 16, 1
	v_add3_u32 v77, v77, v238, s1
	v_bfe_u32 v238, v78, 16, 1
	v_add3_u32 v78, v78, v238, s1
	v_bfe_u32 v238, v79, 16, 1
	v_add3_u32 v79, v79, v238, s1
	v_bfe_u32 v238, v72, 16, 1
	v_add3_u32 v72, v72, v238, s1
	v_bfe_u32 v238, v73, 16, 1
	v_add3_u32 v73, v73, v238, s1
	v_bfe_u32 v238, v74, 16, 1
	v_add3_u32 v74, v74, v238, s1
	v_bfe_u32 v238, v75, 16, 1
	v_add3_u32 v75, v75, v238, s1
	v_cndmask_b32_e32 v220, v76, v77, vcc
	v_cndmask_b32_e32 v224, v77, v76, vcc
	v_cndmask_b32_e32 v221, v78, v79, vcc
	v_cndmask_b32_e32 v225, v79, v78, vcc
	v_cndmask_b32_e32 v222, v72, v73, vcc
	v_cndmask_b32_e32 v226, v73, v72, vcc
	v_cndmask_b32_e32 v223, v74, v75, vcc
	v_cndmask_b32_e32 v227, v75, v74, vcc
	v_lshl_add_u64 v[228:229], v[86:87], 0, v[232:233]
	v_mov_b32_dpp v224, v224 quad_perm:[1,0,3,2] row_mask:0xf bank_mask:0xf
	v_mov_b32_dpp v225, v225 quad_perm:[1,0,3,2] row_mask:0xf bank_mask:0xf
	v_mov_b32_dpp v226, v226 quad_perm:[1,0,3,2] row_mask:0xf bank_mask:0xf
	v_mov_b32_dpp v227, v227 quad_perm:[1,0,3,2] row_mask:0xf bank_mask:0xf
	s_nop 0
	v_perm_b32 v220, v224, v220, v236
	global_store_dword v[228:229], v220, off
	v_lshl_add_u64 v[228:229], v[228:229], 0, v[234:235]
	v_perm_b32 v221, v225, v221, v236
	global_store_dword v[228:229], v221, off
	v_lshl_add_u64 v[228:229], v[228:229], 0, v[234:235]
	v_perm_b32 v222, v226, v222, v236
	global_store_dword v[228:229], v222, off
	v_lshl_add_u64 v[228:229], v[228:229], 0, v[234:235]
	v_perm_b32 v223, v227, v223, v236
	global_store_dword v[228:229], v223, off

.LBB0_1125:
	v_mov_b32_e32 v81, v80
	v_mov_b32_e32 v72, v80
	v_mov_b32_e32 v73, v80
	v_pk_mul_f32 v[70:71], v[70:71], v[72:73]
	v_pk_mul_f32 v[68:69], v[68:69], v[80:81]
	v_pk_mul_f32 v[66:67], v[66:67], v[72:73]
	v_pk_mul_f32 v[64:65], v[64:65], v[80:81]
	s_and_b64 vcc, exec, s[4:5]
	s_mov_b64 s[44:45], -1
	s_cbranch_vccnz .LBB0_1127
	s_add_i32 s14, s14, s51
	s_ashr_i32 s15, s14, 31
	s_lshl_b64 s[14:15], s[14:15], 18
	v_lshl_add_u64 v[72:73], v[138:139], 0, s[14:15]
	v_mov_b32_e32 v85, v145
	v_lshl_add_u64 v[72:73], v[72:73], 0, v[84:85]
	s_movk_i32 s14, 0x1000
	s_movk_i32 s14, 0x2000
	s_movk_i32 s14, 0x3000
	s_movk_i32 s14, 0x4000
	s_mov_b64 s[44:45], 0
	v_cmp_ne_u32_e32 vcc, 0, v237
	v_bfe_u32 v238, v68, 16, 1
	v_add3_u32 v68, v68, v238, s1
	v_bfe_u32 v238, v69, 16, 1
	v_add3_u32 v69, v69, v238, s1
	v_bfe_u32 v238, v70, 16, 1
	v_add3_u32 v70, v70, v238, s1
	v_bfe_u32 v238, v71, 16, 1
	v_add3_u32 v71, v71, v238, s1
	v_bfe_u32 v238, v64, 16, 1
	v_add3_u32 v64, v64, v238, s1
	v_bfe_u32 v238, v65, 16, 1
	v_add3_u32 v65, v65, v238, s1
	v_bfe_u32 v238, v66, 16, 1
	v_add3_u32 v66, v66, v238, s1
	v_bfe_u32 v238, v67, 16, 1
	v_add3_u32 v67, v67, v238, s1
	v_cndmask_b32_e32 v220, v68, v69, vcc
	v_cndmask_b32_e32 v224, v69, v68, vcc
	v_cndmask_b32_e32 v221, v70, v71, vcc
	v_cndmask_b32_e32 v225, v71, v70, vcc
	v_cndmask_b32_e32 v222, v64, v65, vcc
	v_cndmask_b32_e32 v226, v65, v64, vcc
	v_cndmask_b32_e32 v223, v66, v67, vcc
	v_cndmask_b32_e32 v227, v67, v66, vcc
	v_lshl_add_u64 v[228:229], v[72:73], 0, v[232:233]
	v_mov_b32_dpp v224, v224 quad_perm:[1,0,3,2] row_mask:0xf bank_mask:0xf
	v_mov_b32_dpp v225, v225 quad_perm:[1,0,3,2] row_mask:0xf bank_mask:0xf
	v_mov_b32_dpp v226, v226 quad_perm:[1,0,3,2] row_mask:0xf bank_mask:0xf
	v_mov_b32_dpp v227, v227 quad_perm:[1,0,3,2] row_mask:0xf bank_mask:0xf
	s_nop 0
	v_perm_b32 v220, v224, v220, v236
	global_store_dword v[228:229], v220, off
	v_lshl_add_u64 v[228:229], v[228:229], 0, v[234:235]
	v_perm_b32 v221, v225, v221, v236
	global_store_dword v[228:229], v221, off
	v_lshl_add_u64 v[228:229], v[228:229], 0, v[234:235]
	v_perm_b32 v222, v226, v222, v236
	global_store_dword v[228:229], v222, off
	v_lshl_add_u64 v[228:229], v[228:229], 0, v[234:235]
	v_perm_b32 v223, v227, v223, v236
	global_store_dword v[228:229], v223, off

; __device__ __forceinline__ float rstd4(const float* pp, int row, float invn) { const f32x4 a = *(const f32x4*)(pp + (size_t)row * 4); return rsqrtf(((a.x + a.y) + (a.z + a.w)) * invn + 1e-6f); }
.LBB0_1129:
	s_addk_i32 s33, 0x80
	s_ashr_i32 s14, s33, 8
	v_or_b32_e32 v64, s33, v137
	s_and_b32 s14, s14, -8
	v_readlane_b32 s44, v254, 12
	v_ashrrev_i32_e32 v65, 31, v64
	v_readlane_b32 s45, v254, 13
	s_mov_b32 s15, 0x800000
	s_nop 0
	v_lshl_add_u64 v[66:67], v[64:65], 4, s[44:45]
	s_mov_b64 s[44:45], -1
	v_mov_b32_e32 v66, v202
	v_mov_b32_e32 v67, v203
	v_mov_b32_e32 v68, v204
	v_mov_b32_e32 v69, v205
	v_mov_b32_e32 v70, v67
	v_mov_b32_e32 v71, v68
	v_mov_b32_e32 v67, v69
	v_pk_add_f32 v[66:67], v[70:71], v[66:67]
	s_nop 0
	v_add_f32_e32 v65, v66, v67
	v_fmamk_f32 v65, v65, 0x3c000000, v171
	v_cmp_gt_f32_e32 vcc, s15, v65
	v_mul_f32_e32 v66, 0x4b800000, v65
	s_nop 0
	v_cndmask_b32_e32 v65, v65, v66, vcc
	v_rsq_f32_e32 v65, v65
	s_nop 0
	v_mul_f32_e32 v66, 0x45800000, v65
	v_cndmask_b32_e32 v66, v65, v66, vcc
	v_bitop3_b32 v65, s33, v178, v137 bitop3:0xc8
	v_pk_mul_f32 v[62:63], v[62:63], v[66:67] op_sel_hi:[1,0]
	v_pk_mul_f32 v[60:61], v[60:61], v[66:67] op_sel_hi:[1,0]
	v_pk_mul_f32 v[58:59], v[58:59], v[66:67] op_sel_hi:[1,0]
	v_pk_mul_f32 v[56:57], v[56:57], v[66:67] op_sel_hi:[1,0]
	s_and_b64 vcc, exec, s[4:5]
	v_lshlrev_b32_e32 v68, 1, v65
	s_cbranch_vccnz .LBB0_1131
	s_add_i32 s44, s14, s50
	s_ashr_i32 s45, s44, 31
	s_lshl_b64 s[44:45], s[44:45], 18
	v_lshl_add_u64 v[70:71], v[138:139], 0, s[44:45]
	v_mov_b32_e32 v69, v145
	v_lshl_add_u64 v[70:71], v[70:71], 0, v[68:69]
	s_movk_i32 s15, 0x1000
	s_movk_i32 s15, 0x2000
	s_movk_i32 s15, 0x3000
	s_movk_i32 s15, 0x4000
	s_mov_b64 s[44:45], 0
	v_cmp_ne_u32_e32 vcc, 0, v237
	v_bfe_u32 v238, v60, 16, 1
	v_add3_u32 v60, v60, v238, s1
	v_bfe_u32 v238, v61, 16, 1
	v_add3_u32 v61, v61, v238, s1
	v_bfe_u32 v238, v62, 16, 1
	v_add3_u32 v62, v62, v238, s1
	v_bfe_u32 v238, v63, 16, 1
	v_add3_u32 v63, v63, v238, s1
	v_bfe_u32 v238, v56, 16, 1
	v_add3_u32 v56, v56, v238, s1
	v_bfe_u32 v238, v57, 16, 1
	v_add3_u32 v57, v57, v238, s1
	v_bfe_u32 v238, v58, 16, 1
	v_add3_u32 v58, v58, v238, s1
	v_bfe_u32 v238, v59, 16, 1
	v_add3_u32 v59, v59, v238, s1
	v_cndmask_b32_e32 v220, v60, v61, vcc
	v_cndmask_b32_e32 v224, v61, v60, vcc
	v_cndmask_b32_e32 v221, v62, v63, vcc
	v_cndmask_b32_e32 v225, v63, v62, vcc
	v_cndmask_b32_e32 v222, v56, v57, vcc
	v_cndmask_b32_e32 v226, v57, v56, vcc
	v_cndmask_b32_e32 v223, v58, v59, vcc
	v_cndmask_b32_e32 v227, v59, v58, vcc
	v_lshl_add_u64 v[228:229], v[70:71], 0, v[232:233]
	v_mov_b32_dpp v224, v224 quad_perm:[1,0,3,2] row_mask:0xf bank_mask:0xf
	v_mov_b32_dpp v225, v225 quad_perm:[1,0,3,2] row_mask:0xf bank_mask:0xf
	v_mov_b32_dpp v226, v226 quad_perm:[1,0,3,2] row_mask:0xf bank_mask:0xf
	v_mov_b32_dpp v227, v227 quad_perm:[1,0,3,2] row_mask:0xf bank_mask:0xf
	s_nop 0
	v_perm_b32 v220, v224, v220, v236
	global_store_dword v[228:229], v220, off
	v_lshl_add_u64 v[228:229], v[228:229], 0, v[234:235]
	v_perm_b32 v221, v225, v221, v236
	global_store_dword v[228:229], v221, off
	v_lshl_add_u64 v[228:229], v[228:229], 0, v[234:235]
	v_perm_b32 v222, v226, v222, v236
	global_store_dword v[228:229], v222, off
	v_lshl_add_u64 v[228:229], v[228:229], 0, v[234:235]
	v_perm_b32 v223, v227, v223, v236
	global_store_dword v[228:229], v223, off

.LBB0_1133:
	v_mov_b32_e32 v67, v66
	v_mov_b32_e32 v56, v66
	v_mov_b32_e32 v57, v66
	v_pk_mul_f32 v[54:55], v[54:55], v[56:57]
	v_pk_mul_f32 v[52:53], v[52:53], v[66:67]
	v_pk_mul_f32 v[50:51], v[50:51], v[56:57]
	v_pk_mul_f32 v[48:49], v[48:49], v[66:67]
	s_and_b64 vcc, exec, s[4:5]
	s_mov_b64 s[44:45], -1
	s_cbranch_vccnz .LBB0_1135
	s_add_i32 s44, s14, s51
	s_ashr_i32 s45, s44, 31
	s_lshl_b64 s[44:45], s[44:45], 18
	v_lshl_add_u64 v[56:57], v[138:139], 0, s[44:45]
	v_mov_b32_e32 v69, v145
	v_lshl_add_u64 v[56:57], v[56:57], 0, v[68:69]
	s_movk_i32 s15, 0x1000
	s_movk_i32 s15, 0x2000
	s_movk_i32 s15, 0x3000
	s_movk_i32 s15, 0x4000
	s_mov_b64 s[44:45], 0
	v_cmp_ne_u32_e32 vcc, 0, v237
	v_bfe_u32 v238, v52, 16, 1
	v_add3_u32 v52, v52, v238, s1
	v_bfe_u32 v238, v53, 16, 1
	v_add3_u32 v53, v53, v238, s1
	v_bfe_u32 v238, v54, 16, 1
	v_add3_u32 v54, v54, v238, s1
	v_bfe_u32 v238, v55, 16, 1
	v_add3_u32 v55, v55, v238, s1
	v_bfe_u32 v238, v48, 16, 1
	v_add3_u32 v48, v48, v238, s1
	v_bfe_u32 v238, v49, 16, 1
	v_add3_u32 v49, v49, v238, s1
	v_bfe_u32 v238, v50, 16, 1
	v_add3_u32 v50, v50, v238, s1
	v_bfe_u32 v238, v51, 16, 1
	v_add3_u32 v51, v51, v238, s1
	v_cndmask_b32_e32 v220, v52, v53, vcc
	v_cndmask_b32_e32 v224, v53, v52, vcc
	v_cndmask_b32_e32 v221, v54, v55, vcc
	v_cndmask_b32_e32 v225, v55, v54, vcc
	v_cndmask_b32_e32 v222, v48, v49, vcc
	v_cndmask_b32_e32 v226, v49, v48, vcc
	v_cndmask_b32_e32 v223, v50, v51, vcc
	v_cndmask_b32_e32 v227, v51, v50, vcc
	v_lshl_add_u64 v[228:229], v[56:57], 0, v[232:233]
	v_mov_b32_dpp v224, v224 quad_perm:[1,0,3,2] row_mask:0xf bank_mask:0xf
	v_mov_b32_dpp v225, v225 quad_perm:[1,0,3,2] row_mask:0xf bank_mask:0xf
	v_mov_b32_dpp v226, v226 quad_perm:[1,0,3,2] row_mask:0xf bank_mask:0xf
	v_mov_b32_dpp v227, v227 quad_perm:[1,0,3,2] row_mask:0xf bank_mask:0xf
	s_nop 0
	v_perm_b32 v220, v224, v220, v236
	global_store_dword v[228:229], v220, off
	v_lshl_add_u64 v[228:229], v[228:229], 0, v[234:235]
	v_perm_b32 v221, v225, v221, v236
	global_store_dword v[228:229], v221, off
	v_lshl_add_u64 v[228:229], v[228:229], 0, v[234:235]
	v_perm_b32 v222, v226, v222, v236
	global_store_dword v[228:229], v222, off
	v_lshl_add_u64 v[228:229], v[228:229], 0, v[234:235]
	v_perm_b32 v223, v227, v223, v236
	global_store_dword v[228:229], v223, off

; __device__ __forceinline__ float rstd4(const float* pp, int row, float invn) { const f32x4 a = *(const f32x4*)(pp + (size_t)row * 4); return rsqrtf(((a.x + a.y) + (a.z + a.w)) * invn + 1e-6f); }
.LBB0_1137:
	v_or_b32_e32 v50, 16, v64
	v_readlane_b32 s44, v254, 12
	v_ashrrev_i32_e32 v51, 31, v50
	v_readlane_b32 s45, v254, 13
	s_mov_b32 s15, 0x800000
	s_nop 0
	v_lshl_add_u64 v[48:49], v[50:51], 4, s[44:45]
	s_mov_b64 s[44:45], -1
	v_mov_b32_e32 v52, v206
	v_mov_b32_e32 v53, v207
	v_mov_b32_e32 v54, v208
	v_mov_b32_e32 v55, v209
	v_mov_b32_e32 v48, v53
	v_mov_b32_e32 v49, v54
	v_mov_b32_e32 v53, v55
	v_pk_add_f32 v[48:49], v[48:49], v[52:53]
	s_nop 0
	v_add_f32_e32 v48, v48, v49
	v_fmamk_f32 v48, v48, 0x3c000000, v171
	v_cmp_gt_f32_e32 vcc, s15, v48
	v_mul_f32_e32 v49, 0x4b800000, v48
	s_movk_i32 s15, 0x7df
	v_cndmask_b32_e32 v48, v48, v49, vcc
	v_rsq_f32_e32 v48, v48
	s_nop 0
	v_mul_f32_e32 v49, 0x45800000, v48
	v_cndmask_b32_e32 v48, v48, v49, vcc
	v_bitop3_b32 v49, v64, s15, 16 bitop3:0xc8
	v_pk_mul_f32 v[46:47], v[46:47], v[48:49] op_sel_hi:[1,0]
	v_pk_mul_f32 v[44:45], v[44:45], v[48:49] op_sel_hi:[1,0]
	v_pk_mul_f32 v[42:43], v[42:43], v[48:49] op_sel_hi:[1,0]
	v_pk_mul_f32 v[40:41], v[40:41], v[48:49] op_sel_hi:[1,0]
	s_and_b64 vcc, exec, s[4:5]
	v_lshlrev_b32_e32 v52, 1, v49
	s_cbranch_vccnz .LBB0_1139
	s_add_i32 s44, s14, s50
	s_ashr_i32 s45, s44, 31
	s_lshl_b64 s[44:45], s[44:45], 18
	v_lshl_add_u64 v[54:55], v[138:139], 0, s[44:45]
	v_mov_b32_e32 v53, v145
	v_lshl_add_u64 v[54:55], v[54:55], 0, v[52:53]
	s_movk_i32 s15, 0x1000
	s_movk_i32 s15, 0x2000
	s_movk_i32 s15, 0x3000
	s_movk_i32 s15, 0x4000
	s_mov_b64 s[44:45], 0
	v_cmp_ne_u32_e32 vcc, 0, v237
	v_bfe_u32 v238, v44, 16, 1
	v_add3_u32 v44, v44, v238, s1
	v_bfe_u32 v238, v45, 16, 1
	v_add3_u32 v45, v45, v238, s1
	v_bfe_u32 v238, v46, 16, 1
	v_add3_u32 v46, v46, v238, s1
	v_bfe_u32 v238, v47, 16, 1
	v_add3_u32 v47, v47, v238, s1
	v_bfe_u32 v238, v40, 16, 1
	v_add3_u32 v40, v40, v238, s1
	v_bfe_u32 v238, v41, 16, 1
	v_add3_u32 v41, v41, v238, s1
	v_bfe_u32 v238, v42, 16, 1
	v_add3_u32 v42, v42, v238, s1
	v_bfe_u32 v238, v43, 16, 1
	v_add3_u32 v43, v43, v238, s1
	v_cndmask_b32_e32 v220, v44, v45, vcc
	v_cndmask_b32_e32 v224, v45, v44, vcc
	v_cndmask_b32_e32 v221, v46, v47, vcc
	v_cndmask_b32_e32 v225, v47, v46, vcc
	v_cndmask_b32_e32 v222, v40, v41, vcc
	v_cndmask_b32_e32 v226, v41, v40, vcc
	v_cndmask_b32_e32 v223, v42, v43, vcc
	v_cndmask_b32_e32 v227, v43, v42, vcc
	v_lshl_add_u64 v[228:229], v[54:55], 0, v[232:233]
	v_mov_b32_dpp v224, v224 quad_perm:[1,0,3,2] row_mask:0xf bank_mask:0xf
	v_mov_b32_dpp v225, v225 quad_perm:[1,0,3,2] row_mask:0xf bank_mask:0xf
	v_mov_b32_dpp v226, v226 quad_perm:[1,0,3,2] row_mask:0xf bank_mask:0xf
	v_mov_b32_dpp v227, v227 quad_perm:[1,0,3,2] row_mask:0xf bank_mask:0xf
	s_nop 0
	v_perm_b32 v220, v224, v220, v236
	global_store_dword v[228:229], v220, off
	v_lshl_add_u64 v[228:229], v[228:229], 0, v[234:235]
	v_perm_b32 v221, v225, v221, v236
	global_store_dword v[228:229], v221, off
	v_lshl_add_u64 v[228:229], v[228:229], 0, v[234:235]
	v_perm_b32 v222, v226, v222, v236
	global_store_dword v[228:229], v222, off
	v_lshl_add_u64 v[228:229], v[228:229], 0, v[234:235]
	v_perm_b32 v223, v227, v223, v236
	global_store_dword v[228:229], v223, off

.LBB0_1141:
	v_mov_b32_e32 v49, v48
	v_mov_b32_e32 v40, v48
	v_mov_b32_e32 v41, v48
	v_pk_mul_f32 v[38:39], v[38:39], v[40:41]
	v_pk_mul_f32 v[36:37], v[36:37], v[48:49]
	v_pk_mul_f32 v[34:35], v[34:35], v[40:41]
	v_pk_mul_f32 v[32:33], v[32:33], v[48:49]
	s_and_b64 vcc, exec, s[4:5]
	s_mov_b64 s[44:45], -1
	s_cbranch_vccnz .LBB0_1143
	s_add_i32 s44, s14, s51
	s_ashr_i32 s45, s44, 31
	s_lshl_b64 s[44:45], s[44:45], 18
	v_lshl_add_u64 v[40:41], v[138:139], 0, s[44:45]
	v_mov_b32_e32 v53, v145
	v_lshl_add_u64 v[40:41], v[40:41], 0, v[52:53]
	s_movk_i32 s15, 0x1000
	s_movk_i32 s15, 0x2000
	s_movk_i32 s15, 0x3000
	s_movk_i32 s15, 0x4000
	s_mov_b64 s[44:45], 0
	v_cmp_ne_u32_e32 vcc, 0, v237
	v_bfe_u32 v238, v36, 16, 1
	v_add3_u32 v36, v36, v238, s1
	v_bfe_u32 v238, v37, 16, 1
	v_add3_u32 v37, v37, v238, s1
	v_bfe_u32 v238, v38, 16, 1
	v_add3_u32 v38, v38, v238, s1
	v_bfe_u32 v238, v39, 16, 1
	v_add3_u32 v39, v39, v238, s1
	v_bfe_u32 v238, v32, 16, 1
	v_add3_u32 v32, v32, v238, s1
	v_bfe_u32 v238, v33, 16, 1
	v_add3_u32 v33, v33, v238, s1
	v_bfe_u32 v238, v34, 16, 1
	v_add3_u32 v34, v34, v238, s1
	v_bfe_u32 v238, v35, 16, 1
	v_add3_u32 v35, v35, v238, s1
	v_cndmask_b32_e32 v220, v36, v37, vcc
	v_cndmask_b32_e32 v224, v37, v36, vcc
	v_cndmask_b32_e32 v221, v38, v39, vcc
	v_cndmask_b32_e32 v225, v39, v38, vcc
	v_cndmask_b32_e32 v222, v32, v33, vcc
	v_cndmask_b32_e32 v226, v33, v32, vcc
	v_cndmask_b32_e32 v223, v34, v35, vcc
	v_cndmask_b32_e32 v227, v35, v34, vcc
	v_lshl_add_u64 v[228:229], v[40:41], 0, v[232:233]
	v_mov_b32_dpp v224, v224 quad_perm:[1,0,3,2] row_mask:0xf bank_mask:0xf
	v_mov_b32_dpp v225, v225 quad_perm:[1,0,3,2] row_mask:0xf bank_mask:0xf
	v_mov_b32_dpp v226, v226 quad_perm:[1,0,3,2] row_mask:0xf bank_mask:0xf
	v_mov_b32_dpp v227, v227 quad_perm:[1,0,3,2] row_mask:0xf bank_mask:0xf
	s_nop 0
	v_perm_b32 v220, v224, v220, v236
	global_store_dword v[228:229], v220, off
	v_lshl_add_u64 v[228:229], v[228:229], 0, v[234:235]
	v_perm_b32 v221, v225, v221, v236
	global_store_dword v[228:229], v221, off
	v_lshl_add_u64 v[228:229], v[228:229], 0, v[234:235]
	v_perm_b32 v222, v226, v222, v236
	global_store_dword v[228:229], v222, off
	v_lshl_add_u64 v[228:229], v[228:229], 0, v[234:235]
	v_perm_b32 v223, v227, v223, v236
	global_store_dword v[228:229], v223, off

; __device__ __forceinline__ float rstd4(const float* pp, int row, float invn) { const f32x4 a = *(const f32x4*)(pp + (size_t)row * 4); return rsqrtf(((a.x + a.y) + (a.z + a.w)) * invn + 1e-6f); }
.LBB0_1145:
	v_or_b32_e32 v34, 32, v64
	v_readlane_b32 s44, v254, 12
	v_ashrrev_i32_e32 v35, 31, v34
	v_readlane_b32 s45, v254, 13
	s_mov_b32 s15, 0x800000
	s_nop 0
	v_lshl_add_u64 v[32:33], v[34:35], 4, s[44:45]
	s_mov_b64 s[44:45], -1
	v_mov_b32_e32 v36, v210
	v_mov_b32_e32 v37, v211
	v_mov_b32_e32 v38, v212
	v_mov_b32_e32 v39, v213
	v_mov_b32_e32 v32, v37
	v_mov_b32_e32 v33, v38
	v_mov_b32_e32 v37, v39
	v_pk_add_f32 v[32:33], v[32:33], v[36:37]
	s_nop 0
	v_add_f32_e32 v32, v32, v33
	v_fmamk_f32 v32, v32, 0x3c000000, v171
	v_cmp_gt_f32_e32 vcc, s15, v32
	v_mul_f32_e32 v33, 0x4b800000, v32
	s_movk_i32 s15, 0x7ef
	v_cndmask_b32_e32 v32, v32, v33, vcc
	v_rsq_f32_e32 v32, v32
	s_nop 0
	v_mul_f32_e32 v33, 0x45800000, v32
	v_cndmask_b32_e32 v32, v32, v33, vcc
	v_bitop3_b32 v33, v64, s15, 32 bitop3:0xc8
	v_pk_mul_f32 v[30:31], v[30:31], v[32:33] op_sel_hi:[1,0]
	v_pk_mul_f32 v[28:29], v[28:29], v[32:33] op_sel_hi:[1,0]
	v_pk_mul_f32 v[26:27], v[26:27], v[32:33] op_sel_hi:[1,0]
	v_pk_mul_f32 v[24:25], v[24:25], v[32:33] op_sel_hi:[1,0]
	s_and_b64 vcc, exec, s[4:5]
	v_lshlrev_b32_e32 v36, 1, v33
	s_cbranch_vccnz .LBB0_1147
	s_add_i32 s44, s14, s50
	s_ashr_i32 s45, s44, 31
	s_lshl_b64 s[44:45], s[44:45], 18
	v_lshl_add_u64 v[38:39], v[138:139], 0, s[44:45]
	v_mov_b32_e32 v37, v145
	v_lshl_add_u64 v[38:39], v[38:39], 0, v[36:37]
	s_movk_i32 s15, 0x1000
	s_movk_i32 s15, 0x2000
	s_movk_i32 s15, 0x3000
	s_movk_i32 s15, 0x4000
	s_mov_b64 s[44:45], 0
	v_cmp_ne_u32_e32 vcc, 0, v237
	v_bfe_u32 v238, v28, 16, 1
	v_add3_u32 v28, v28, v238, s1
	v_bfe_u32 v238, v29, 16, 1
	v_add3_u32 v29, v29, v238, s1
	v_bfe_u32 v238, v30, 16, 1
	v_add3_u32 v30, v30, v238, s1
	v_bfe_u32 v238, v31, 16, 1
	v_add3_u32 v31, v31, v238, s1
	v_bfe_u32 v238, v24, 16, 1
	v_add3_u32 v24, v24, v238, s1
	v_bfe_u32 v238, v25, 16, 1
	v_add3_u32 v25, v25, v238, s1
	v_bfe_u32 v238, v26, 16, 1
	v_add3_u32 v26, v26, v238, s1
	v_bfe_u32 v238, v27, 16, 1
	v_add3_u32 v27, v27, v238, s1
	v_cndmask_b32_e32 v220, v28, v29, vcc
	v_cndmask_b32_e32 v224, v29, v28, vcc
	v_cndmask_b32_e32 v221, v30, v31, vcc
	v_cndmask_b32_e32 v225, v31, v30, vcc
	v_cndmask_b32_e32 v222, v24, v25, vcc
	v_cndmask_b32_e32 v226, v25, v24, vcc
	v_cndmask_b32_e32 v223, v26, v27, vcc
	v_cndmask_b32_e32 v227, v27, v26, vcc
	v_lshl_add_u64 v[228:229], v[38:39], 0, v[232:233]
	v_mov_b32_dpp v224, v224 quad_perm:[1,0,3,2] row_mask:0xf bank_mask:0xf
	v_mov_b32_dpp v225, v225 quad_perm:[1,0,3,2] row_mask:0xf bank_mask:0xf
	v_mov_b32_dpp v226, v226 quad_perm:[1,0,3,2] row_mask:0xf bank_mask:0xf
	v_mov_b32_dpp v227, v227 quad_perm:[1,0,3,2] row_mask:0xf bank_mask:0xf
	s_nop 0
	v_perm_b32 v220, v224, v220, v236
	global_store_dword v[228:229], v220, off
	v_lshl_add_u64 v[228:229], v[228:229], 0, v[234:235]
	v_perm_b32 v221, v225, v221, v236
	global_store_dword v[228:229], v221, off
	v_lshl_add_u64 v[228:229], v[228:229], 0, v[234:235]
	v_perm_b32 v222, v226, v222, v236
	global_store_dword v[228:229], v222, off
	v_lshl_add_u64 v[228:229], v[228:229], 0, v[234:235]
	v_perm_b32 v223, v227, v223, v236
	global_store_dword v[228:229], v223, off

.LBB0_1149:
	v_mov_b32_e32 v33, v32
	v_mov_b32_e32 v24, v32
	v_mov_b32_e32 v25, v32
	v_pk_mul_f32 v[22:23], v[22:23], v[24:25]
	v_pk_mul_f32 v[20:21], v[20:21], v[32:33]
	v_pk_mul_f32 v[18:19], v[18:19], v[24:25]
	v_pk_mul_f32 v[16:17], v[16:17], v[32:33]
	s_and_b64 vcc, exec, s[4:5]
	s_mov_b64 s[44:45], -1
	s_cbranch_vccnz .LBB0_1151
	s_add_i32 s44, s14, s51
	s_ashr_i32 s45, s44, 31
	s_lshl_b64 s[44:45], s[44:45], 18
	v_lshl_add_u64 v[24:25], v[138:139], 0, s[44:45]
	v_mov_b32_e32 v37, v145
	v_lshl_add_u64 v[24:25], v[24:25], 0, v[36:37]
	s_movk_i32 s15, 0x1000
	s_movk_i32 s15, 0x2000
	s_movk_i32 s15, 0x3000
	s_movk_i32 s15, 0x4000
	s_mov_b64 s[44:45], 0
	v_cmp_ne_u32_e32 vcc, 0, v237
	v_bfe_u32 v238, v20, 16, 1
	v_add3_u32 v20, v20, v238, s1
	v_bfe_u32 v238, v21, 16, 1
	v_add3_u32 v21, v21, v238, s1
	v_bfe_u32 v238, v22, 16, 1
	v_add3_u32 v22, v22, v238, s1
	v_bfe_u32 v238, v23, 16, 1
	v_add3_u32 v23, v23, v238, s1
	v_bfe_u32 v238, v16, 16, 1
	v_add3_u32 v16, v16, v238, s1
	v_bfe_u32 v238, v17, 16, 1
	v_add3_u32 v17, v17, v238, s1
	v_bfe_u32 v238, v18, 16, 1
	v_add3_u32 v18, v18, v238, s1
	v_bfe_u32 v238, v19, 16, 1
	v_add3_u32 v19, v19, v238, s1
	v_cndmask_b32_e32 v220, v20, v21, vcc
	v_cndmask_b32_e32 v224, v21, v20, vcc
	v_cndmask_b32_e32 v221, v22, v23, vcc
	v_cndmask_b32_e32 v225, v23, v22, vcc
	v_cndmask_b32_e32 v222, v16, v17, vcc
	v_cndmask_b32_e32 v226, v17, v16, vcc
	v_cndmask_b32_e32 v223, v18, v19, vcc
	v_cndmask_b32_e32 v227, v19, v18, vcc
	v_lshl_add_u64 v[228:229], v[24:25], 0, v[232:233]
	v_mov_b32_dpp v224, v224 quad_perm:[1,0,3,2] row_mask:0xf bank_mask:0xf
	v_mov_b32_dpp v225, v225 quad_perm:[1,0,3,2] row_mask:0xf bank_mask:0xf
	v_mov_b32_dpp v226, v226 quad_perm:[1,0,3,2] row_mask:0xf bank_mask:0xf
	v_mov_b32_dpp v227, v227 quad_perm:[1,0,3,2] row_mask:0xf bank_mask:0xf
	s_nop 0
	v_perm_b32 v220, v224, v220, v236
	global_store_dword v[228:229], v220, off
	v_lshl_add_u64 v[228:229], v[228:229], 0, v[234:235]
	v_perm_b32 v221, v225, v221, v236
	global_store_dword v[228:229], v221, off
	v_lshl_add_u64 v[228:229], v[228:229], 0, v[234:235]
	v_perm_b32 v222, v226, v222, v236
	global_store_dword v[228:229], v222, off
	v_lshl_add_u64 v[228:229], v[228:229], 0, v[234:235]
	v_perm_b32 v223, v227, v223, v236
	global_store_dword v[228:229], v223, off

; __device__ __forceinline__ float rstd4(const float* pp, int row, float invn) { const f32x4 a = *(const f32x4*)(pp + (size_t)row * 4); return rsqrtf(((a.x + a.y) + (a.z + a.w)) * invn + 1e-6f); }
.LBB0_1153:
	v_or_b32_e32 v18, 48, v64
	v_readlane_b32 s44, v254, 12
	v_ashrrev_i32_e32 v19, 31, v18
	v_readlane_b32 s45, v254, 13
	s_mov_b32 s15, 0x800000
	s_nop 0
	v_lshl_add_u64 v[16:17], v[18:19], 4, s[44:45]
	s_mov_b64 s[44:45], -1
	v_mov_b32_e32 v20, v214
	v_mov_b32_e32 v21, v215
	v_mov_b32_e32 v22, v216
	v_mov_b32_e32 v23, v217
	v_mov_b32_e32 v16, v21
	v_mov_b32_e32 v17, v22
	v_mov_b32_e32 v21, v23
	v_pk_add_f32 v[16:17], v[16:17], v[20:21]
	s_nop 0
	v_add_f32_e32 v16, v16, v17
	v_fmamk_f32 v16, v16, 0x3c000000, v171
	v_cmp_gt_f32_e32 vcc, s15, v16
	v_mul_f32_e32 v17, 0x4b800000, v16
	s_movk_i32 s15, 0x7ff
	v_cndmask_b32_e32 v16, v16, v17, vcc
	v_rsq_f32_e32 v16, v16
	s_nop 0
	v_mul_f32_e32 v17, 0x45800000, v16
	v_cndmask_b32_e32 v16, v16, v17, vcc
	v_bitop3_b32 v17, v64, s15, 48 bitop3:0xc8
	v_pk_mul_f32 v[14:15], v[14:15], v[16:17] op_sel_hi:[1,0]
	v_pk_mul_f32 v[12:13], v[12:13], v[16:17] op_sel_hi:[1,0]
	v_pk_mul_f32 v[10:11], v[10:11], v[16:17] op_sel_hi:[1,0]
	v_pk_mul_f32 v[8:9], v[8:9], v[16:17] op_sel_hi:[1,0]
	s_and_b64 vcc, exec, s[4:5]
	v_lshlrev_b32_e32 v20, 1, v17
	s_cbranch_vccnz .LBB0_1155
	s_add_i32 s44, s14, s50
	s_ashr_i32 s45, s44, 31
	s_lshl_b64 s[44:45], s[44:45], 18
	v_lshl_add_u64 v[22:23], v[138:139], 0, s[44:45]
	v_mov_b32_e32 v21, v145
	v_lshl_add_u64 v[22:23], v[22:23], 0, v[20:21]
	s_movk_i32 s15, 0x1000
	s_movk_i32 s15, 0x2000
	s_movk_i32 s15, 0x3000
	s_movk_i32 s15, 0x4000
	s_mov_b64 s[44:45], 0
	v_cmp_ne_u32_e32 vcc, 0, v237
	v_bfe_u32 v238, v12, 16, 1
	v_add3_u32 v12, v12, v238, s1
	v_bfe_u32 v238, v13, 16, 1
	v_add3_u32 v13, v13, v238, s1
	v_bfe_u32 v238, v14, 16, 1
	v_add3_u32 v14, v14, v238, s1
	v_bfe_u32 v238, v15, 16, 1
	v_add3_u32 v15, v15, v238, s1
	v_bfe_u32 v238, v8, 16, 1
	v_add3_u32 v8, v8, v238, s1
	v_bfe_u32 v238, v9, 16, 1
	v_add3_u32 v9, v9, v238, s1
	v_bfe_u32 v238, v10, 16, 1
	v_add3_u32 v10, v10, v238, s1
	v_bfe_u32 v238, v11, 16, 1
	v_add3_u32 v11, v11, v238, s1
	v_cndmask_b32_e32 v220, v12, v13, vcc
	v_cndmask_b32_e32 v224, v13, v12, vcc
	v_cndmask_b32_e32 v221, v14, v15, vcc
	v_cndmask_b32_e32 v225, v15, v14, vcc
	v_cndmask_b32_e32 v222, v8, v9, vcc
	v_cndmask_b32_e32 v226, v9, v8, vcc
	v_cndmask_b32_e32 v223, v10, v11, vcc
	v_cndmask_b32_e32 v227, v11, v10, vcc
	v_lshl_add_u64 v[228:229], v[22:23], 0, v[232:233]
	v_mov_b32_dpp v224, v224 quad_perm:[1,0,3,2] row_mask:0xf bank_mask:0xf
	v_mov_b32_dpp v225, v225 quad_perm:[1,0,3,2] row_mask:0xf bank_mask:0xf
	v_mov_b32_dpp v226, v226 quad_perm:[1,0,3,2] row_mask:0xf bank_mask:0xf
	v_mov_b32_dpp v227, v227 quad_perm:[1,0,3,2] row_mask:0xf bank_mask:0xf
	s_nop 0
	v_perm_b32 v220, v224, v220, v236
	global_store_dword v[228:229], v220, off
	v_lshl_add_u64 v[228:229], v[228:229], 0, v[234:235]
	v_perm_b32 v221, v225, v221, v236
	global_store_dword v[228:229], v221, off
	v_lshl_add_u64 v[228:229], v[228:229], 0, v[234:235]
	v_perm_b32 v222, v226, v222, v236
	global_store_dword v[228:229], v222, off
	v_lshl_add_u64 v[228:229], v[228:229], 0, v[234:235]
	v_perm_b32 v223, v227, v223, v236
	global_store_dword v[228:229], v223, off

.LBB0_1160:
	s_add_i32 s4, s14, s51
	s_ashr_i32 s5, s4, 31
	s_lshl_b64 s[4:5], s[4:5], 18
	v_lshl_add_u64 v[8:9], v[138:139], 0, s[4:5]
	v_mov_b32_e32 v21, v145
	v_lshl_add_u64 v[8:9], v[8:9], 0, v[20:21]
	s_movk_i32 s4, 0x1000
	s_movk_i32 s4, 0x2000
	s_movk_i32 s4, 0x3000
	s_movk_i32 s4, 0x4000
	v_cmp_ne_u32_e32 vcc, 0, v237
	v_bfe_u32 v238, v4, 16, 1
	v_add3_u32 v4, v4, v238, s1
	v_bfe_u32 v238, v5, 16, 1
	v_add3_u32 v5, v5, v238, s1
	v_bfe_u32 v238, v6, 16, 1
	v_add3_u32 v6, v6, v238, s1
	v_bfe_u32 v238, v7, 16, 1
	v_add3_u32 v7, v7, v238, s1
	v_bfe_u32 v238, v0, 16, 1
	v_add3_u32 v0, v0, v238, s1
	v_bfe_u32 v238, v1, 16, 1
	v_add3_u32 v1, v1, v238, s1
	v_bfe_u32 v238, v2, 16, 1
	v_add3_u32 v2, v2, v238, s1
	v_bfe_u32 v238, v3, 16, 1
	v_add3_u32 v3, v3, v238, s1
	v_cndmask_b32_e32 v220, v4, v5, vcc
	v_cndmask_b32_e32 v224, v5, v4, vcc
	v_cndmask_b32_e32 v221, v6, v7, vcc
	v_cndmask_b32_e32 v225, v7, v6, vcc
	v_cndmask_b32_e32 v222, v0, v1, vcc
	v_cndmask_b32_e32 v226, v1, v0, vcc
	v_cndmask_b32_e32 v223, v2, v3, vcc
	v_cndmask_b32_e32 v227, v3, v2, vcc
	v_lshl_add_u64 v[228:229], v[8:9], 0, v[232:233]
	v_mov_b32_dpp v224, v224 quad_perm:[1,0,3,2] row_mask:0xf bank_mask:0xf
	v_mov_b32_dpp v225, v225 quad_perm:[1,0,3,2] row_mask:0xf bank_mask:0xf
	v_mov_b32_dpp v226, v226 quad_perm:[1,0,3,2] row_mask:0xf bank_mask:0xf
	v_mov_b32_dpp v227, v227 quad_perm:[1,0,3,2] row_mask:0xf bank_mask:0xf
	s_nop 0
	v_perm_b32 v220, v224, v220, v236
	global_store_dword v[228:229], v220, off
	v_lshl_add_u64 v[228:229], v[228:229], 0, v[234:235]
	v_perm_b32 v221, v225, v221, v236
	global_store_dword v[228:229], v221, off
	v_lshl_add_u64 v[228:229], v[228:229], 0, v[234:235]
	v_perm_b32 v222, v226, v222, v236
	global_store_dword v[228:229], v222, off
	v_lshl_add_u64 v[228:229], v[228:229], 0, v[234:235]
	v_perm_b32 v223, v227, v223, v236
	global_store_dword v[228:229], v223, off
	s_cbranch_execnz .LBB0_1159
